# static priority variant: one s_setprio 1 for waves 0-3 per GEMM phase, flips deleted
# speedup vs baseline: 1.0080x; 1.0080x over previous
; #define PG8_STAGE(bufoff, gbase, voff) do { _Pragma("unroll") for (int _i = 0; _i < 2; ++_i) \
;         __builtin_amdgcn_global_load_lds((const unsigned*)((const char*)(gbase) + (voff)[_i]), (PG8_LAS unsigned*)(lds + (bufoff) + ldsw + _i * 8192), 16, 0, 0); } while (0)
; #define PG8_WAIT_V(n) asm volatile("s_waitcnt vmcnt(" #n ")" ::: "memory")
; #define PG8_BAR __builtin_amdgcn_s_barrier()
; template <class Epi, class Sched, bool ALIGN_EPI = false, bool SP2 = false>
; __device__ __forceinline__ void gemm_phase(PG8_LAS unsigned char* lds, const Gemm g, const Sched& S, const Epi& E) {
;     ...
;     for (int i = 0; i < 2; ++i) { int R, C; stage_rc(tid * 16 + i * 8192, R, C); const int Rb = Epi::PERM ? ((R & ~31) + perm32(R & 31)) : R;
;         voffA[i] = (unsigned)(R * K + C) * 2u; voffB[i] = (unsigned)(Rb * K + C) * 2u; }
;     const size_t kstep = (size_t)(BK * 2);
;     const size_t hstep = (size_t)HALF * K * 2;
;     const size_t tstep = 2 * hstep;
;     const unsigned ldsw = (unsigned)wid * 1024u;
;     const int aoff = lds_byte(wr * 64 + fr, fq * 8), boff = lds_byte(wc * 32 + fr, fq * 8);
;     ...
;         PG8_STAGE(PG8_SB(0, 0), cB, voffB); PG8_STAGE(PG8_SB(0, 1), cB + hstep, voffB); PG8_STAGE(PG8_SA(0, 0), cA, voffA); PG8_STAGE(PG8_SA(0, 1), cA + hstep, voffA);
;         if (wr == 1) PG8_BAR;
;         PG8_WAIT_V(2); PG8_BAR;
;         PG8_STAGE(PG8_SB(1, 0), cB + kstep, voffB); PG8_STAGE(PG8_SA(1, 0), cA + kstep, voffA); PG8_STAGE(PG8_SB(1, 1), cB + hstep + kstep, voffB);
;         PG8_WAIT_V(6); PG8_BAR;
.LBB0_186:
	s_lshl_b32 s4, s4, 5
	s_and_b32 s14, s4, 0x60
	s_mov_b64 s[4:5], 0x80
	s_add_i32 m0, s21, 0x18000
	v_lshl_add_u64 v[6:7], v[6:7], 0, s[4:5]
	s_lshl_b32 s7, s6, 13
	s_lshl_b32 s15, s14, 7
	s_waitcnt vmcnt(2)
	s_barrier
	global_load_lds_dwordx4 v[6:7], off
	v_lshl_add_u64 v[4:5], v[4:5], 0, s[4:5]
	s_add_i32 m0, s21, 0x1a000
	s_add_i32 s42, s21, 0x8000
	s_add_i32 s43, s21, 0xa000
	global_load_lds_dwordx4 v[4:5], off
	v_lshl_add_u64 v[0:1], v[0:1], 0, s[4:5]
	s_mov_b32 m0, s42
	s_add_u32 s8, s24, 0x40080
	global_load_lds_dwordx4 v[0:1], off
	v_lshl_add_u64 v[0:1], v[2:3], 0, s[4:5]
	s_mov_b32 m0, s43
	s_addc_u32 s9, s25, 0
	global_load_lds_dwordx4 v[0:1], off
	s_add_i32 m0, s21, 0x1c000
	v_lshl_add_u64 v[0:1], s[8:9], 0, v[132:133]
	global_load_lds_dwordx4 v[0:1], off
	v_lshl_add_u64 v[0:1], s[8:9], 0, v[128:129]
	s_add_i32 m0, s21, 0x1e000
	s_cmpk_lt_u32 s1, 0x100
	global_load_lds_dwordx4 v[0:1], off
	v_lshrrev_b32_e32 v1, 1, v9
	v_and_b32_e32 v1, 24, v1
	v_and_b32_e32 v0, 15, v9
	v_lshlrev_b32_e32 v2, 1, v1
	v_lshl_or_b32 v144, s6, 6, v0
	v_lshl_or_b32 v0, v0, 6, v2
	v_lshlrev_b32_e32 v2, 2, v9
	v_and_b32_e32 v2, 32, v2
	v_bitop3_b32 v3, v0, s7, v2 bitop3:0xde
	v_bitop3_b32 v145, v0, s15, v2 bitop3:0xde
	v_lshlrev_b32_e32 v0, 14, v13
	v_and_b32_e32 v0, 0xffff8000, v0
	v_or_b32_e32 v146, s14, v1
	v_lshl_add_u32 v0, v12, 11, v0
	v_and_b32_e32 v1, 1, v13
	v_lshl_or_b32 v0, v1, 6, v0
	v_lshl_add_u32 v136, v14, 1, v0
	v_lshlrev_b32_e32 v0, 14, v8
	v_and_b32_e32 v0, 0xffff8000, v0
	s_waitcnt vmcnt(0)
	v_lshl_add_u32 v0, v10, 11, v0
	v_and_b32_e32 v1, 1, v8
	s_sext_i32_i8 s49, s0
	s_cselect_b64 s[6:7], -1, 0
	v_readlane_b32 s0, v235, 6
	v_lshl_or_b32 v0, v1, 6, v0
	s_add_i32 s46, 0, 0x10000
	s_add_i32 s47, 0, 0x14000
	s_ashr_i32 s44, s0, 31
	s_mov_b32 s45, s0
	v_mov_b32_e32 v137, v133
	v_lshl_add_u32 v138, v11, 1, v0
	v_mov_b32_e32 v139, v133
	v_mov_b64_e32 v[140:141], 0xb00
	v_mov_b64_e32 v[142:143], 0xaff
	v_add_u32_e32 v147, s46, v145
	v_add_u32_e32 v148, s47, v145
	v_add_u32_e32 v149, 0, v3
	s_movk_i32 s48, 0x1600
	s_barrier
	v_readlane_b32 s1, v235, 7
	s_mov_b32 s98, 0
	v_readfirstlane_b32 s99, v189
	s_nop 0
	s_lshr_b32 s99, s99, 6
	s_cmp_ge_u32 s99, 4
	s_cbranch_scc1 .Lprio_189
	s_setprio 1

; #define PG8_STAGE(bufoff, gbase, voff) do { _Pragma("unroll") for (int _i = 0; _i < 2; ++_i) \
;         __builtin_amdgcn_global_load_lds((const unsigned*)((const char*)(gbase) + (voff)[_i]), (PG8_LAS unsigned*)(lds + (bufoff) + ldsw + _i * 8192), 16, 0, 0); } while (0)
; #define PG8_WAIT_V(n) asm volatile("s_waitcnt vmcnt(" #n ")" ::: "memory")
; #define PG8_BAR __builtin_amdgcn_s_barrier()
; template <class Epi, class Sched, bool ALIGN_EPI = false, bool SP2 = false>
; __device__ __forceinline__ void gemm_phase(PG8_LAS unsigned char* lds, const Gemm g, const Sched& S, const Epi& E) {
;     ...
;     for (int i = 0; i < 2; ++i) { int R, C; stage_rc(tid * 16 + i * 8192, R, C); const int Rb = Epi::PERM ? ((R & ~31) + perm32(R & 31)) : R;
;         voffA[i] = (unsigned)(R * K + C) * 2u; voffB[i] = (unsigned)(Rb * K + C) * 2u; }
;     const size_t kstep = (size_t)(BK * 2);
;     const size_t hstep = (size_t)HALF * K * 2;
;     const size_t tstep = 2 * hstep;
;     const unsigned ldsw = (unsigned)wid * 1024u;
;     const int aoff = lds_byte(wr * 64 + fr, fq * 8), boff = lds_byte(wc * 32 + fr, fq * 8);
;     ...
;         PG8_STAGE(PG8_SB(0, 0), cB, voffB); PG8_STAGE(PG8_SB(0, 1), cB + hstep, voffB); PG8_STAGE(PG8_SA(0, 0), cA, voffA); PG8_STAGE(PG8_SA(0, 1), cA + hstep, voffA);
;         if (wr == 1) PG8_BAR;
;         PG8_WAIT_V(2); PG8_BAR;
;         PG8_STAGE(PG8_SB(1, 0), cB + kstep, voffB); PG8_STAGE(PG8_SA(1, 0), cA + kstep, voffA); PG8_STAGE(PG8_SB(1, 1), cB + hstep + kstep, voffB);
;         PG8_WAIT_V(6); PG8_BAR;
.LBB0_260:
	s_lshl_b32 s5, s5, 5
	s_mov_b64 s[14:15], 0x80
	s_and_b32 s18, s5, 0x60
	s_add_i32 m0, s42, 0x18000
	v_lshl_add_u64 v[6:7], v[6:7], 0, s[14:15]
	s_lshl_b32 s16, s0, 13
	s_lshl_b32 s5, s18, 7
	s_waitcnt vmcnt(2)
	s_barrier
	global_load_lds_dwordx4 v[6:7], off
	v_lshl_add_u64 v[4:5], v[4:5], 0, s[14:15]
	s_add_i32 m0, s42, 0x1a000
	s_add_i32 s47, s42, 0x8000
	s_add_i32 s48, s42, 0xa000
	global_load_lds_dwordx4 v[4:5], off
	v_lshl_add_u64 v[0:1], v[0:1], 0, s[14:15]
	s_mov_b32 m0, s47
	s_add_u32 s6, s34, 0xb0080
	global_load_lds_dwordx4 v[0:1], off
	v_lshl_add_u64 v[0:1], v[2:3], 0, s[14:15]
	s_mov_b32 m0, s48
	s_addc_u32 s7, s35, 0
	global_load_lds_dwordx4 v[0:1], off
	s_add_i32 m0, s42, 0x1c000
	v_lshl_add_u64 v[0:1], s[6:7], 0, v[138:139]
	global_load_lds_dwordx4 v[0:1], off
	v_lshl_add_u64 v[0:1], s[6:7], 0, v[142:143]
	s_add_i32 m0, s42, 0x1e000
	s_cmpk_lt_u32 s4, 0x100
	global_load_lds_dwordx4 v[0:1], off
	v_bfe_u32 v1, v8, 4, 2
	v_and_b32_e32 v0, 15, v8
	v_lshlrev_b32_e32 v2, 4, v1
	v_lshl_or_b32 v158, s0, 6, v0
	v_lshl_or_b32 v0, v0, 6, v2
	v_lshlrev_b32_e32 v2, 2, v8
	v_and_b32_e32 v2, 32, v2
	v_readlane_b32 s0, v235, 0
	v_bitop3_b32 v3, v0, s16, v2 bitop3:0xde
	v_bitop3_b32 v159, v0, s5, v2 bitop3:0xde
	s_cselect_b64 s[16:17], -1, 0
	v_cmp_eq_u32_e64 s[4:5], 0, v1
	s_ashr_i32 s51, s0, 31
	v_lshl_or_b32 v160, v1, 3, s18
	v_lshrrev_b32_e32 v1, 1, v9
	v_mul_lo_u32 v0, v11, s1
	s_mov_b32 s0, 0xb000
	v_mad_u64_u32 v[0:1], s[18:19], v1, s0, v[0:1]
	v_or_b32_e32 v0, v0, v10
	s_mov_b64 s[6:7], 0xb0080
	v_add_lshl_u32 v0, v0, v12, 1
	v_mov_b32_e32 v1, v139
	v_lshl_add_u64 v[144:145], v[0:1], 0, s[6:7]
	v_lshrrev_b32_e32 v1, 1, v13
	v_mul_lo_u32 v0, v14, s1
	v_mad_u64_u32 v[0:1], s[0:1], v1, s0, v[0:1]
	s_waitcnt vmcnt(6)
	v_readlane_b32 s20, v235, 6
	v_or_b32_e32 v0, v0, v15
	v_readlane_b32 s21, v235, 7
	v_add_lshl_u32 v0, v0, v16, 1
	v_mov_b32_e32 v1, v139
	s_add_i32 s52, 0, 0x10000
	s_add_i32 s53, 0, 0x14000
	s_ashr_i32 s49, s20, 31
	s_mov_b32 s50, s20
	v_lshl_add_u64 v[146:147], v[0:1], 0, s[6:7]
	v_mov_b64_e32 v[148:149], 0x200
	v_mov_b64_e32 v[150:151], 0x1ff
	v_add_u32_e32 v161, s52, v159
	v_add_u32_e32 v162, s53, v159
	v_add_u32_e32 v163, 0, v3
	s_mov_b64 s[18:19], 0x20000
	s_mov_b64 s[20:21], 0x24000
	s_mov_b64 s[22:23], 0x28000
	s_mov_b64 s[24:25], 0x2c000
	v_mbcnt_hi_u32_b32 v164, -1, v190
	s_barrier
	v_readfirstlane_b32 s99, v189
	s_nop 0
	s_lshr_b32 s99, s99, 6
	s_cmp_ge_u32 s99, 4
	s_cbranch_scc1 .Lprio_263
	s_setprio 1

; #define PG8_STAGE(bufoff, gbase, voff) do { _Pragma("unroll") for (int _i = 0; _i < 2; ++_i) \
;         __builtin_amdgcn_global_load_lds((const unsigned*)((const char*)(gbase) + (voff)[_i]), (PG8_LAS unsigned*)(lds + (bufoff) + ldsw + _i * 8192), 16, 0, 0); } while (0)
; #define PG8_WAIT_V(n) asm volatile("s_waitcnt vmcnt(" #n ")" ::: "memory")
; #define PG8_BAR __builtin_amdgcn_s_barrier()
; template <class Epi, class Sched, bool ALIGN_EPI = false, bool SP2 = false>
; __device__ __forceinline__ void gemm_phase(PG8_LAS unsigned char* lds, const Gemm g, const Sched& S, const Epi& E) {
;     ...
;     for (int i = 0; i < 2; ++i) { int R, C; stage_rc(tid * 16 + i * 8192, R, C); const int Rb = Epi::PERM ? ((R & ~31) + perm32(R & 31)) : R;
;         voffA[i] = (unsigned)(R * K + C) * 2u; voffB[i] = (unsigned)(Rb * K + C) * 2u; }
;     const size_t kstep = (size_t)(BK * 2);
;     const size_t hstep = (size_t)HALF * K * 2;
;     const size_t tstep = 2 * hstep;
;     const unsigned ldsw = (unsigned)wid * 1024u;
;     const int aoff = lds_byte(wr * 64 + fr, fq * 8), boff = lds_byte(wc * 32 + fr, fq * 8);
;     ...
;         PG8_STAGE(PG8_SB(0, 0), cB, voffB); PG8_STAGE(PG8_SB(0, 1), cB + hstep, voffB); PG8_STAGE(PG8_SA(0, 0), cA, voffA); PG8_STAGE(PG8_SA(0, 1), cA + hstep, voffA);
;         if (wr == 1) PG8_BAR;
;         PG8_WAIT_V(2); PG8_BAR;
;         PG8_STAGE(PG8_SB(1, 0), cB + kstep, voffB); PG8_STAGE(PG8_SA(1, 0), cA + kstep, voffA); PG8_STAGE(PG8_SB(1, 1), cB + hstep + kstep, voffB);
;         PG8_WAIT_V(6); PG8_BAR;
.LBB0_368:
	s_mov_b64 s[16:17], 0x80
	s_and_b32 s1, s6, 3
	s_add_i32 m0, s44, 0x18000
	v_lshl_add_u64 v[6:7], v[6:7], 0, s[16:17]
	s_lshl_b32 s12, s7, 13
	s_lshl_b32 s24, s1, 5
	s_lshl_b32 s20, s1, 12
	s_waitcnt vmcnt(2)
	s_barrier
	global_load_lds_dwordx4 v[6:7], off
	v_lshl_add_u64 v[4:5], v[4:5], 0, s[16:17]
	s_add_i32 m0, s44, 0x1a000
	s_add_i32 s48, s44, 0x8000
	s_add_i32 s49, s44, 0xa000
	global_load_lds_dwordx4 v[4:5], off
	v_lshl_add_u64 v[0:1], v[0:1], 0, s[16:17]
	s_mov_b32 m0, s48
	s_add_u32 s18, s38, 0x40080
	global_load_lds_dwordx4 v[0:1], off
	v_lshl_add_u64 v[0:1], v[2:3], 0, s[16:17]
	s_mov_b32 m0, s49
	s_addc_u32 s19, s39, 0
	global_load_lds_dwordx4 v[0:1], off
	s_add_i32 m0, s44, 0x1c000
	v_lshl_add_u64 v[0:1], s[18:19], 0, v[148:149]
	global_load_lds_dwordx4 v[0:1], off
	v_lshl_add_u64 v[0:1], s[18:19], 0, v[144:145]
	s_add_i32 m0, s44, 0x1e000
	v_bfe_u32 v2, v10, 4, 2
	global_load_lds_dwordx4 v[0:1], off
	v_lshrrev_b32_e32 v0, 4, v10
	v_and_b32_e32 v1, 15, v10
	v_lshlrev_b32_e32 v154, 3, v2
	v_lshlrev_b32_e32 v2, 4, v2
	v_bitop3_b32 v0, s6, v0, 3 bitop3:0xa8
	s_sext_i32_i8 s57, s4
	v_lshl_or_b32 v155, s7, 6, v1
	v_lshl_or_b32 v1, v1, 6, v2
	v_lshlrev_b32_e32 v2, 2, v10
	s_cmpk_lt_u32 s5, 0x100
	v_cmp_eq_u32_e64 s[4:5], 0, v0
	v_lshlrev_b32_e32 v0, 14, v13
	v_and_b32_e32 v2, 32, v2
	v_and_b32_e32 v0, 0xffff8000, v0
	v_bitop3_b32 v3, v1, s12, v2 bitop3:0xde
	v_bitop3_b32 v170, v1, s20, v2 bitop3:0xde
	v_lshl_add_u32 v0, v12, 11, v0
	v_and_b32_e32 v1, 1, v13
	v_lshl_or_b32 v0, v1, 6, v0
	v_lshl_add_u32 v156, v14, 1, v0
	v_lshlrev_b32_e32 v0, 14, v8
	v_and_b32_e32 v0, 0xffff8000, v0
	s_waitcnt vmcnt(6)
	v_lshl_add_u32 v0, v9, 11, v0
	v_and_b32_e32 v1, 1, v8
	s_cselect_b64 s[18:19], -1, 0
	s_lshl_b32 s1, s1, 6
	v_readlane_b32 s6, v235, 6
	v_lshl_or_b32 v0, v1, 6, v0
	s_add_i32 s52, 0, 0x10000
	s_add_i32 s53, 0, 0x14000
	s_ashr_i32 s50, s6, 31
	s_mov_b32 s51, s6
	v_mov_b32_e32 v157, v153
	v_lshl_add_u32 v158, v11, 1, v0
	v_mov_b32_e32 v159, v153
	v_mov_b64_e32 v[160:161], 0x700
	v_mov_b64_e32 v[162:163], 0x6ff
	v_add_u32_e32 v171, s52, v170
	v_add_u32_e32 v172, s53, v170
	v_add_u32_e32 v173, 0, v3
	v_mov_b32_e32 v174, 0x358637bd
	s_mov_b32 s54, 0x800000
	s_mov_b64 s[20:21], 0x1400
	s_mov_b64 s[22:23], 0x1600
	s_movk_i32 s55, 0x1c00
	s_lshl_b32 s24, s24, 1
	s_lshl_b32 s12, s1, 1
	v_mov_b32_e32 v175, 0x3e38aa3b
	v_mbcnt_hi_u32_b32 v176, -1, v190
	s_mov_b32 s56, s13
	s_barrier
	v_readlane_b32 s7, v235, 7
	v_readfirstlane_b32 s99, v189
	s_nop 0
	s_lshr_b32 s99, s99, 6
	s_cmp_ge_u32 s99, 4
	s_cbranch_scc1 .Lprio_371
	s_setprio 1

; #define PG8_STAGE(bufoff, gbase, voff) do { _Pragma("unroll") for (int _i = 0; _i < 2; ++_i) \
;         __builtin_amdgcn_global_load_lds((const unsigned*)((const char*)(gbase) + (voff)[_i]), (PG8_LAS unsigned*)(lds + (bufoff) + ldsw + _i * 8192), 16, 0, 0); } while (0)
; #define PG8_WAIT_V(n) asm volatile("s_waitcnt vmcnt(" #n ")" ::: "memory")
; #define PG8_BAR __builtin_amdgcn_s_barrier()
; template <class Epi, class Sched, bool ALIGN_EPI = false, bool SP2 = false>
; __device__ __forceinline__ void gemm_phase(PG8_LAS unsigned char* lds, const Gemm g, const Sched& S, const Epi& E) {
;     ...
;     for (int i = 0; i < 2; ++i) { int R, C; stage_rc(tid * 16 + i * 8192, R, C); const int Rb = Epi::PERM ? ((R & ~31) + perm32(R & 31)) : R;
;         voffA[i] = (unsigned)(R * K + C) * 2u; voffB[i] = (unsigned)(Rb * K + C) * 2u; }
;     const size_t kstep = (size_t)(BK * 2);
;     const size_t hstep = (size_t)HALF * K * 2;
;     const size_t tstep = 2 * hstep;
;     const unsigned ldsw = (unsigned)wid * 1024u;
;     const int aoff = lds_byte(wr * 64 + fr, fq * 8), boff = lds_byte(wc * 32 + fr, fq * 8);
;     ...
;         PG8_STAGE(PG8_SB(0, 0), cB, voffB); PG8_STAGE(PG8_SB(0, 1), cB + hstep, voffB); PG8_STAGE(PG8_SA(0, 0), cA, voffA); PG8_STAGE(PG8_SA(0, 1), cA + hstep, voffA);
;         if (wr == 1) PG8_BAR;
;         PG8_WAIT_V(2); PG8_BAR;
;         PG8_STAGE(PG8_SB(1, 0), cB + kstep, voffB); PG8_STAGE(PG8_SA(1, 0), cA + kstep, voffA); PG8_STAGE(PG8_SB(1, 1), cB + hstep + kstep, voffB);
;         PG8_WAIT_V(6); PG8_BAR;
.LBB0_688:
	s_lshl_b32 s2, s2, 5
	s_and_b32 s14, s2, 0x60
	s_mov_b64 s[2:3], 0x80
	s_add_i32 m0, s25, 0x18000
	v_lshl_add_u64 v[6:7], v[6:7], 0, s[2:3]
	s_lshl_b32 s12, s5, 13
	s_lshl_b32 s13, s14, 7
	s_waitcnt vmcnt(2)
	s_barrier
	global_load_lds_dwordx4 v[6:7], off
	v_lshl_add_u64 v[4:5], v[4:5], 0, s[2:3]
	s_add_i32 m0, s25, 0x1a000
	s_add_i32 s40, s25, 0x8000
	s_add_i32 s41, s25, 0xa000
	global_load_lds_dwordx4 v[4:5], off
	v_lshl_add_u64 v[0:1], v[0:1], 0, s[2:3]
	s_mov_b32 m0, s40
	s_add_u32 s6, s28, 0x40080
	global_load_lds_dwordx4 v[0:1], off
	v_lshl_add_u64 v[0:1], v[2:3], 0, s[2:3]
	s_mov_b32 m0, s41
	s_addc_u32 s7, s29, 0
	global_load_lds_dwordx4 v[0:1], off
	s_add_i32 m0, s25, 0x1c000
	v_lshl_add_u64 v[0:1], s[6:7], 0, v[130:131]
	global_load_lds_dwordx4 v[0:1], off
	v_lshl_add_u64 v[0:1], s[6:7], 0, v[134:135]
	s_add_i32 m0, s25, 0x1e000
	s_cmpk_lt_u32 s4, 0x100
	global_load_lds_dwordx4 v[0:1], off
	v_bfe_u32 v1, v8, 4, 2
	v_and_b32_e32 v0, 15, v8
	v_lshlrev_b32_e32 v2, 4, v1
	v_lshl_or_b32 v148, s5, 6, v0
	v_lshl_or_b32 v0, v0, 6, v2
	v_lshlrev_b32_e32 v2, 2, v8
	v_and_b32_e32 v2, 32, v2
	v_bitop3_b32 v3, v0, s12, v2 bitop3:0xde
	v_bitop3_b32 v149, v0, s13, v2 bitop3:0xde
	v_lshlrev_b32_e32 v0, 14, v9
	v_and_b32_e32 v0, 0xffff8000, v0
	v_cmp_eq_u32_e64 s[4:5], 0, v1
	v_lshl_or_b32 v150, v1, 3, s14
	v_lshl_add_u32 v0, v10, 11, v0
	v_and_b32_e32 v1, 1, v9
	v_lshl_or_b32 v0, v1, 6, v0
	v_lshl_add_u32 v136, v11, 1, v0
	v_lshlrev_b32_e32 v0, 14, v12
	v_and_b32_e32 v0, 0xffff8000, v0
	s_waitcnt vmcnt(6)
	v_readlane_b32 s6, v235, 6
	v_lshl_add_u32 v0, v13, 11, v0
	v_and_b32_e32 v1, 1, v12
	s_cselect_b64 s[12:13], -1, 0
	s_ashr_i32 s42, s6, 31
	s_mov_b32 s43, s6
	v_readlane_b32 s6, v235, 0
	v_lshl_or_b32 v0, v1, 6, v0
	s_add_i32 s45, 0, 0x10000
	s_add_i32 s46, 0, 0x14000
	s_ashr_i32 s44, s6, 31
	v_mov_b32_e32 v137, v131
	v_lshl_add_u32 v138, v14, 1, v0
	v_mov_b32_e32 v139, v131
	v_mov_b64_e32 v[140:141], 0x200
	v_mov_b64_e32 v[142:143], 0x1ff
	v_add_u32_e32 v151, s45, v149
	v_add_u32_e32 v152, s46, v149
	v_add_u32_e32 v153, 0, v3
	v_mbcnt_hi_u32_b32 v154, -1, v190
	s_barrier
	v_readlane_b32 s7, v235, 7
	v_readfirstlane_b32 s99, v189
	s_nop 0
	s_lshr_b32 s99, s99, 6
	s_cmp_ge_u32 s99, 4
	s_cbranch_scc1 .Lprio_691
	s_setprio 1

; #define PG8_STAGE(bufoff, gbase, voff) do { _Pragma("unroll") for (int _i = 0; _i < 2; ++_i) \
;         __builtin_amdgcn_global_load_lds((const unsigned*)((const char*)(gbase) + (voff)[_i]), (PG8_LAS unsigned*)(lds + (bufoff) + ldsw + _i * 8192), 16, 0, 0); } while (0)
; #define PG8_WAIT_V(n) asm volatile("s_waitcnt vmcnt(" #n ")" ::: "memory")
; #define PG8_BAR __builtin_amdgcn_s_barrier()
; template <class Epi, class Sched, bool ALIGN_EPI = false, bool SP2 = false>
; __device__ __forceinline__ void gemm_phase(PG8_LAS unsigned char* lds, const Gemm g, const Sched& S, const Epi& E) {
;     ...
;     for (int i = 0; i < 2; ++i) { int R, C; stage_rc(tid * 16 + i * 8192, R, C); const int Rb = Epi::PERM ? ((R & ~31) + perm32(R & 31)) : R;
;         voffA[i] = (unsigned)(R * K + C) * 2u; voffB[i] = (unsigned)(Rb * K + C) * 2u; }
;     const size_t kstep = (size_t)(BK * 2);
;     const size_t hstep = (size_t)HALF * K * 2;
;     const size_t tstep = 2 * hstep;
;     const unsigned ldsw = (unsigned)wid * 1024u;
;     const int aoff = lds_byte(wr * 64 + fr, fq * 8), boff = lds_byte(wc * 32 + fr, fq * 8);
;     ...
;         PG8_STAGE(PG8_SB(0, 0), cB, voffB); PG8_STAGE(PG8_SB(0, 1), cB + hstep, voffB); PG8_STAGE(PG8_SA(0, 0), cA, voffA); PG8_STAGE(PG8_SA(0, 1), cA + hstep, voffA);
;         if (wr == 1) PG8_BAR;
;         PG8_WAIT_V(2); PG8_BAR;
;         PG8_STAGE(PG8_SB(1, 0), cB + kstep, voffB); PG8_STAGE(PG8_SA(1, 0), cA + kstep, voffA); PG8_STAGE(PG8_SB(1, 1), cB + hstep + kstep, voffB);
;         PG8_WAIT_V(6); PG8_BAR;
.LBB0_776:
	s_lshl_b32 s1, s6, 5
	s_mov_b64 s[6:7], 0x80
	s_and_b32 s16, s1, 0x60
	s_add_i32 m0, s34, 0x18000
	v_lshl_add_u64 v[6:7], v[6:7], 0, s[6:7]
	s_lshl_b32 s13, s12, 13
	s_lshl_b32 s17, s16, 7
	s_waitcnt vmcnt(2)
	s_barrier
	global_load_lds_dwordx4 v[6:7], off
	v_lshl_add_u64 v[4:5], v[4:5], 0, s[6:7]
	s_add_i32 m0, s34, 0x1a000
	s_add_i32 s39, s34, 0x8000
	s_add_i32 s40, s34, 0xa000
	global_load_lds_dwordx4 v[4:5], off
	v_lshl_add_u64 v[0:1], v[0:1], 0, s[6:7]
	s_mov_b32 m0, s39
	s_add_u32 s14, s24, 0x40080
	global_load_lds_dwordx4 v[0:1], off
	v_lshl_add_u64 v[0:1], v[2:3], 0, s[6:7]
	s_mov_b32 m0, s40
	s_addc_u32 s15, s25, 0
	global_load_lds_dwordx4 v[0:1], off
	s_add_i32 m0, s34, 0x1c000
	v_lshl_add_u64 v[0:1], s[14:15], 0, v[132:133]
	global_load_lds_dwordx4 v[0:1], off
	v_lshl_add_u64 v[0:1], s[14:15], 0, v[128:129]
	s_add_i32 m0, s34, 0x1e000
	s_cmpk_lt_u32 s5, 0x100
	global_load_lds_dwordx4 v[0:1], off
	v_lshrrev_b32_e32 v1, 1, v9
	v_and_b32_e32 v1, 24, v1
	v_and_b32_e32 v0, 15, v9
	v_lshlrev_b32_e32 v2, 1, v1
	v_lshl_or_b32 v148, s12, 6, v0
	v_lshl_or_b32 v0, v0, 6, v2
	v_lshlrev_b32_e32 v2, 2, v9
	v_and_b32_e32 v2, 32, v2
	v_bitop3_b32 v3, v0, s13, v2 bitop3:0xde
	v_bitop3_b32 v149, v0, s17, v2 bitop3:0xde
	v_lshlrev_b32_e32 v0, 14, v13
	v_and_b32_e32 v0, 0xffff8000, v0
	v_or_b32_e32 v150, s16, v1
	v_lshl_add_u32 v0, v12, 11, v0
	v_and_b32_e32 v1, 1, v13
	v_lshl_or_b32 v0, v1, 6, v0
	v_lshl_add_u32 v136, v14, 1, v0
	v_lshlrev_b32_e32 v0, 14, v8
	v_and_b32_e32 v0, 0xffff8000, v0
	s_waitcnt vmcnt(0)
	v_lshl_add_u32 v0, v10, 11, v0
	v_and_b32_e32 v1, 1, v8
	s_sext_i32_i8 s1, s4
	s_cselect_b64 s[12:13], -1, 0
	v_readlane_b32 s4, v235, 6
	v_lshl_or_b32 v0, v1, 6, v0
	s_add_i32 s43, 0, 0x10000
	s_add_i32 s44, 0, 0x14000
	s_ashr_i32 s41, s4, 31
	s_mov_b32 s42, s4
	v_mov_b32_e32 v137, v133
	v_lshl_add_u32 v138, v11, 1, v0
	v_mov_b32_e32 v139, v133
	v_mov_b64_e32 v[140:141], 0xb00
	v_mov_b64_e32 v[142:143], 0xaff
	v_add_u32_e32 v151, s43, v149
	v_add_u32_e32 v152, s44, v149
	v_add_u32_e32 v153, 0, v3
	v_mov_b32_e32 v154, 0x358637bd
	s_mov_b32 s45, 0x800000
	s_movk_i32 s46, 0x1600
	s_barrier
	v_readlane_b32 s5, v235, 7
	v_readfirstlane_b32 s99, v189
	s_nop 0
	s_lshr_b32 s99, s99, 6
	s_cmp_ge_u32 s99, 4
	s_cbranch_scc1 .Lprio_779
	s_setprio 1

; #define PG8_STAGE(bufoff, gbase, voff) do { _Pragma("unroll") for (int _i = 0; _i < 2; ++_i) \
;         __builtin_amdgcn_global_load_lds((const unsigned*)((const char*)(gbase) + (voff)[_i]), (PG8_LAS unsigned*)(lds + (bufoff) + ldsw + _i * 8192), 16, 0, 0); } while (0)
; #define PG8_WAIT_V(n) asm volatile("s_waitcnt vmcnt(" #n ")" ::: "memory")
; #define PG8_BAR __builtin_amdgcn_s_barrier()
; template <class Epi, class Sched, bool ALIGN_EPI = false, bool SP2 = false>
; __device__ __forceinline__ void gemm_phase(PG8_LAS unsigned char* lds, const Gemm g, const Sched& S, const Epi& E) {
;     ...
;     for (int i = 0; i < 2; ++i) { int R, C; stage_rc(tid * 16 + i * 8192, R, C); const int Rb = Epi::PERM ? ((R & ~31) + perm32(R & 31)) : R;
;         voffA[i] = (unsigned)(R * K + C) * 2u; voffB[i] = (unsigned)(Rb * K + C) * 2u; }
;     const size_t kstep = (size_t)(BK * 2);
;     const size_t hstep = (size_t)HALF * K * 2;
;     const size_t tstep = 2 * hstep;
;     const unsigned ldsw = (unsigned)wid * 1024u;
;     const int aoff = lds_byte(wr * 64 + fr, fq * 8), boff = lds_byte(wc * 32 + fr, fq * 8);
;     ...
;         PG8_STAGE(PG8_SB(0, 0), cB, voffB); PG8_STAGE(PG8_SB(0, 1), cB + hstep, voffB); PG8_STAGE(PG8_SA(0, 0), cA, voffA); PG8_STAGE(PG8_SA(0, 1), cA + hstep, voffA);
;         if (wr == 1) PG8_BAR;
;         PG8_WAIT_V(2); PG8_BAR;
;         PG8_STAGE(PG8_SB(1, 0), cB + kstep, voffB); PG8_STAGE(PG8_SA(1, 0), cA + kstep, voffA); PG8_STAGE(PG8_SB(1, 1), cB + hstep + kstep, voffB);
;         PG8_WAIT_V(6); PG8_BAR;
.LBB0_848:
	s_lshl_b32 s6, s6, 5
	s_and_b32 s14, s6, 0x60
	s_mov_b64 s[6:7], 0x80
	s_add_i32 m0, s35, 0x18000
	v_lshl_add_u64 v[6:7], v[6:7], 0, s[6:7]
	s_lshl_b32 s12, s0, 13
	s_lshl_b32 s13, s14, 7
	s_waitcnt vmcnt(2)
	s_barrier
	global_load_lds_dwordx4 v[6:7], off
	v_lshl_add_u64 v[4:5], v[4:5], 0, s[6:7]
	s_add_i32 m0, s35, 0x1a000
	s_add_i32 s40, s35, 0x8000
	s_add_i32 s41, s35, 0xa000
	global_load_lds_dwordx4 v[4:5], off
	v_lshl_add_u64 v[0:1], v[0:1], 0, s[6:7]
	s_mov_b32 m0, s40
	s_add_u32 s10, s24, 0xb0080
	global_load_lds_dwordx4 v[0:1], off
	v_lshl_add_u64 v[0:1], v[2:3], 0, s[6:7]
	s_mov_b32 m0, s41
	s_addc_u32 s11, s25, 0
	global_load_lds_dwordx4 v[0:1], off
	s_add_i32 m0, s35, 0x1c000
	v_lshl_add_u64 v[0:1], s[10:11], 0, v[130:131]
	global_load_lds_dwordx4 v[0:1], off
	v_lshl_add_u64 v[0:1], s[10:11], 0, v[134:135]
	s_add_i32 m0, s35, 0x1e000
	s_sext_i32_i8 s48, s5
	global_load_lds_dwordx4 v[0:1], off
	v_bfe_u32 v1, v189, 4, 2
	v_and_b32_e32 v0, 15, v189
	v_lshlrev_b32_e32 v2, 4, v1
	v_lshl_or_b32 v150, s0, 6, v0
	v_lshl_or_b32 v0, v0, 6, v2
	v_lshlrev_b32_e32 v2, 2, v189
	v_and_b32_e32 v2, 32, v2
	s_cmpk_lt_u32 s4, 0x100
	v_readlane_b32 s4, v235, 6
	v_bitop3_b32 v3, v0, s12, v2 bitop3:0xde
	v_bitop3_b32 v151, v0, s13, v2 bitop3:0xde
	v_readlane_b32 s5, v235, 7
	v_lshl_or_b32 v152, v1, 3, s14
	v_lshrrev_b32_e32 v1, 1, v8
	v_mul_lo_u32 v0, v10, s1
	s_mov_b32 s0, 0xb000
	s_cselect_b64 s[10:11], -1, 0
	s_ashr_i32 s42, s4, 31
	v_mad_u64_u32 v[0:1], s[4:5], v1, s0, v[0:1]
	v_or_b32_e32 v0, v0, v9
	s_mov_b64 s[12:13], 0xb0080
	v_add_lshl_u32 v0, v0, v11, 1
	v_mov_b32_e32 v1, v131
	v_lshl_add_u64 v[136:137], v[0:1], 0, s[12:13]
	v_lshrrev_b32_e32 v1, 1, v12
	v_mul_lo_u32 v0, v13, s1
	v_mad_u64_u32 v[0:1], s[0:1], v1, s0, v[0:1]
	s_waitcnt vmcnt(6)
	v_or_b32_e32 v0, v0, v14
	v_add_lshl_u32 v0, v0, v15, 1
	v_mov_b32_e32 v1, v131
	s_add_i32 s43, 0, 0x10000
	s_add_i32 s44, 0, 0x14000
	v_lshl_add_u64 v[138:139], v[0:1], 0, s[12:13]
	v_mov_b64_e32 v[140:141], 0x200
	v_mov_b64_e32 v[142:143], 0x1ff
	v_add_u32_e32 v153, s43, v151
	v_add_u32_e32 v154, s44, v151
	v_add_u32_e32 v155, 0, v3
	s_mov_b64 s[12:13], 0x20000
	s_mov_b64 s[14:15], 0x24000
	s_mov_b64 s[16:17], 0x28000
	s_mov_b64 s[18:19], 0x2c000
	s_barrier
	v_readfirstlane_b32 s99, v189
	s_nop 0
	s_lshr_b32 s99, s99, 6
	s_cmp_ge_u32 s99, 4
	s_cbranch_scc1 .Lprio_851
	s_setprio 1
